# EpiStore epilogue: drain vmcnt only when row/col scale loads were issued (wait moved to its consumer); plain-store GEMMs no longer stall on the next tile's in-flight LDS-DMA prefetch
# baseline (speedup 1.0000x reference)
;     DI void operator()(AccRef acc, const Unit& u, int wr, int wc, int fr, int fq) const {
;     ...
;         for (int bj = 0; bj < 2; ++bj) { cs[bj][0] = (f32x4){1.f, 1.f, 1.f, 1.f}; cs[bj][1] = cs[bj][0];
;             if (rs_mode == 2) { cs[bj][0] = *(const f32x4*)(rs + col0 + bj * 128); cs[bj][1] = *(const f32x4*)(rs + col0 + bj * 128 + 4); } }
.LBB0_669:
	s_and_b64 vcc, exec, s[8:9]
	s_cbranch_vccnz .LBB0_671
	global_load_dwordx4 v[158:161], v[154:155], off offset:528
	s_nop 0
	global_load_dwordx4 v[154:157], v[154:155], off offset:512
	s_waitcnt vmcnt(0)
	s_branch .LBB0_672

; DI unsigned pk2(float lo, float hi) { f32x2 v = {lo, hi}; bf16x2_t b = __builtin_convertvector(v, bf16x2_t); return __builtin_bit_cast(unsigned, b); }
;     DI void operator()(AccRef acc, const Unit& u, int wr, int wc, int fr, int fq) const {
;         const int row0 = u.pm * 256 + wr * 64 + fr, col0 = u.pn * 256 + wc * 32 + 8 * fq;
;         f32x4 cs[2][2];
; #pragma unroll
;         for (int bj = 0; bj < 2; ++bj) { cs[bj][0] = (f32x4){1.f, 1.f, 1.f, 1.f}; cs[bj][1] = cs[bj][0];
;             if (rs_mode == 2) { cs[bj][0] = *(const f32x4*)(rs + col0 + bj * 128); cs[bj][1] = *(const f32x4*)(rs + col0 + bj * 128 + 4); } }
; #pragma unroll
;         for (int ai = 0; ai < 2; ++ai)
; #pragma unroll
;             for (int m = 0; m < 4; ++m) { const int row = row0 + ai * 128 + m * 16; bf16_t* rowp = O + (size_t)row * ldc + col0;
;                 const float rr = (rs_mode == 1) ? rs[row] : 1.f;
; #pragma unroll
;                 for (int bj = 0; bj < 2; ++bj) { const f32x4 v0 = acc[ai][bj][m][0] * cs[bj][0] * rr, v1 = acc[ai][bj][m][1] * cs[bj][1] * rr;
;                     u32x4 w; w.x = pk2(v0[0], v0[1]); w.y = pk2(v0[2], v0[3]); w.z = pk2(v1[0], v1[1]); w.w = pk2(v1[2], v1[3]);
;                     *(u32x4*)(rowp + bj * 128) = w; } }
.LBB0_672:
	v_readlane_b32 s4, v253, 21
	v_lshl_add_u32 v182, s43, 8, v169
	v_readlane_b32 s5, v253, 22
	v_ashrrev_i32_e32 v183, 31, v182
	v_mov_b32_e32 v186, 1.0
	v_cndmask_b32_e64 v184, 0, 1, s[4:5]
	v_cmp_ne_u32_e64 s[8:9], 1, v184
	s_andn2_b64 vcc, exec, s[4:5]
	v_lshl_add_u64 v[184:185], v[182:183], 2, s[2:3]
	v_mov_b32_e32 v188, 1.0
	s_cbranch_vccnz .LBB0_674
	global_load_dword v188, v[184:185], off
	global_load_dword v196, v[184:185], off offset:64
	global_load_dword v197, v[184:185], off offset:128
	global_load_dword v198, v[184:185], off offset:192
	global_load_dword v199, v[184:185], off offset:512
	global_load_dword v200, v[184:185], off offset:576
	global_load_dword v201, v[184:185], off offset:640
	global_load_dword v202, v[184:185], off offset:704
	s_waitcnt vmcnt(0)
.LBB0_674:
	v_mad_u64_u32 v[192:193], s[4:5], v182, s60, 0
	v_mov_b32_e32 v194, v193
	v_mad_u64_u32 v[194:195], s[4:5], v183, s60, v[194:195]
	v_mov_b32_e32 v193, v194
	v_pk_mul_f32 v[136:137], v[136:137], v[148:149]
	v_pk_mul_f32 v[134:135], v[134:135], v[146:147]
	v_pk_mul_f32 v[132:133], v[132:133], v[152:153]
	v_pk_mul_f32 v[130:131], v[130:131], v[150:151]
	v_lshl_add_u64 v[192:193], v[192:193], 1, s[50:51]
	v_pk_mul_f32 v[136:137], v[136:137], v[188:189] op_sel_hi:[1,0]
	v_pk_mul_f32 v[134:135], v[134:135], v[188:189] op_sel_hi:[1,0]
	v_pk_mul_f32 v[194:195], v[132:133], v[188:189] op_sel_hi:[1,0]
	v_pk_mul_f32 v[132:133], v[130:131], v[188:189] op_sel_hi:[1,0]
	v_lshl_add_u64 v[192:193], v[180:181], 1, v[192:193]
	v_cvt_pk_bf16_f32 v130, v134, v135
	v_cvt_pk_bf16_f32 v131, v136, v137
	v_cvt_pk_bf16_f32 v132, v132, v133
	v_cvt_pk_bf16_f32 v133, v194, v195
	global_store_dwordx4 v[192:193], v[130:133], off
	v_pk_mul_f32 v[136:137], v[138:139], v[158:159]
	s_and_b64 vcc, exec, s[8:9]
	v_pk_mul_f32 v[130:131], v[144:145], v[156:157]
	v_pk_mul_f32 v[132:133], v[142:143], v[154:155]
	v_pk_mul_f32 v[134:135], v[130:131], v[188:189] op_sel_hi:[1,0]
	v_pk_mul_f32 v[130:131], v[132:133], v[188:189] op_sel_hi:[1,0]
	v_pk_mul_f32 v[132:133], v[140:141], v[160:161]
	v_cvt_pk_bf16_f32 v130, v130, v131
	v_pk_mul_f32 v[138:139], v[132:133], v[188:189] op_sel_hi:[1,0]
	v_pk_mul_f32 v[132:133], v[136:137], v[188:189] op_sel_hi:[1,0]
	v_cvt_pk_bf16_f32 v131, v134, v135
	v_cvt_pk_bf16_f32 v132, v132, v133
	v_cvt_pk_bf16_f32 v133, v138, v139
	global_store_dwordx4 v[192:193], v[130:133], off offset:256
	s_cbranch_vccnz .LBB0_676
	v_mov_b32_e32 v186, v196
